# M1 phase: non-temporal hint on once-read Z (k,v rows) loads
# speedup vs baseline: 1.0009x; 1.0009x over previous
.LBB0_351:
	s_or_b64 exec, exec, s[0:1]
	s_ashr_i32 s0, s90, 8
	s_and_b32 s4, s90, 63
	s_ashr_i32 s1, s0, 31
	s_lshl_b64 s[0:1], s[0:1], 12
	s_lshl_b32 s2, s4, 6
	s_or_b32 s0, s0, s2
	s_mul_i32 s2, s1, 0x2c00
	s_mul_hi_u32 s3, s0, 0x2c00
	s_bfe_u32 s12, s90, 0x20006
	s_add_i32 s3, s3, s2
	s_mul_i32 s2, s0, 0x2c00
	v_readlane_b32 s8, v246, 26
	v_readlane_b32 s9, v246, 27
	s_add_u32 s13, s8, s2
	v_lshlrev_b32_e32 v0, 3, v69
	s_addc_u32 s14, s9, s3
	s_lshl_b32 s2, s12, 8
	v_and_b32_e32 v0, 0x78, v0
	s_add_u32 s2, s13, s2
	v_ashrrev_i32_e32 v6, 3, v69
	s_addc_u32 s3, s14, 0
	v_mov_b32_e32 v65, 0
	v_lshlrev_b32_e32 v64, 1, v0
	v_and_b32_e32 v2, -2, v6
	v_lshl_add_u64 v[0:1], s[2:3], 0, v[64:65]
	s_mov_b64 s[2:3], 0x1000
	s_cmp_lg_u32 s4, 0
	v_mov_b32_e32 v42, v65
	v_mov_b32_e32 v43, v65
	v_lshl_add_u64 v[0:1], v[0:1], 0, s[2:3]
	s_cselect_b64 s[2:3], -1, 0
	v_cmp_lt_i32_e32 vcc, 2, v2
	v_mov_b32_e32 v40, v65
	v_mov_b32_e32 v41, v65
	v_mov_b64_e32 v[58:59], v[42:43]
	s_movk_i32 s6, 0x2c00
	s_or_b64 s[8:9], s[2:3], vcc
	v_add_u32_e32 v3, -3, v2
	v_mov_b64_e32 v[56:57], v[40:41]
	s_and_saveexec_b64 s[4:5], s[8:9]
	s_cbranch_execz .LBB0_353
	v_mad_i64_i32 v[4:5], s[6:7], v3, s6, v[0:1]
	global_load_dwordx4 v[56:59], v[4:5], off nt
.LBB0_353:
	s_or_b64 exec, exec, s[4:5]
	v_cmp_lt_i32_e64 s[6:7], 1, v6
	v_mov_b64_e32 v[50:51], v[42:43]
	s_or_b64 s[8:9], s[2:3], s[6:7]
	v_add_u32_e32 v5, -2, v2
	v_add_u32_e32 v4, -1, v2
	v_mov_b64_e32 v[48:49], v[40:41]
	s_and_saveexec_b64 s[4:5], s[8:9]
	s_cbranch_execz .LBB0_355
	s_movk_i32 s10, 0x2c00
	v_mad_i64_i32 v[8:9], s[8:9], v5, s10, v[0:1]
	v_mad_i64_i32 v[10:11], s[8:9], v4, s10, v[0:1]
	global_load_dwordx4 v[40:43], v[8:9], off nt
	global_load_dwordx4 v[48:51], v[10:11], off nt
.LBB0_355:
	s_or_b64 exec, exec, s[4:5]
	v_mov_b32_e32 v44, 0
	v_mov_b32_e32 v46, v44
	v_mov_b32_e32 v47, v44
	v_cmp_lt_i32_e64 s[8:9], -1, v6
	v_mov_b32_e32 v45, v44
	v_mov_b64_e32 v[54:55], v[46:47]
	s_lshl_b32 s19, s12, 7
	s_or_b64 s[2:3], s[2:3], s[8:9]
	v_mov_b64_e32 v[52:53], v[44:45]
	s_and_saveexec_b64 s[4:5], s[2:3]
	s_cbranch_execz .LBB0_357
	s_movk_i32 s10, 0x2c00
	v_mad_i64_i32 v[8:9], s[10:11], v2, s10, v[0:1]
	global_load_dwordx4 v[52:55], v[8:9], off nt
.LBB0_357:
	s_or_b64 exec, exec, s[4:5]
	v_or_b32_e32 v6, 1, v6
	s_movk_i32 s15, 0x2c00
	v_mad_i64_i32 v[66:67], s[4:5], v6, s15, 0
	s_mov_b32 s5, 0
	s_and_saveexec_b64 s[10:11], s[2:3]
	s_cbranch_execz .LBB0_359
	v_lshl_add_u64 v[0:1], v[0:1], 0, v[66:67]
	global_load_dwordx4 v[44:47], v[0:1], off nt
.LBB0_359:
	s_or_b64 exec, exec, s[10:11]
	v_and_b32_e32 v68, 63, v69
	s_lshl_b32 s2, s19, 1
	s_add_u32 s2, s13, s2
	v_mov_b32_e32 v0, 0
	v_or_b32_e32 v10, s0, v68
	v_mov_b32_e32 v11, s1
	v_readlane_b32 s0, v246, 24
	s_addc_u32 s3, s14, 0
	v_mov_b32_e32 v65, v0
	v_lshlrev_b64 v[10:11], 5, v[10:11]
	v_readlane_b32 s1, v246, 25
	v_lshl_add_u64 v[6:7], s[2:3], 0, v[64:65]
	s_mov_b64 s[10:11], 0x1400
	v_lshl_add_u64 v[10:11], s[0:1], 0, v[10:11]
	s_lshl_b32 s4, s12, 2
	v_lshl_add_u64 v[6:7], v[6:7], 0, s[10:11]
	v_lshl_add_u64 v[10:11], v[10:11], 0, s[4:5]
	v_mad_i64_i32 v[8:9], s[2:3], v2, s15, v[6:7]
	v_lshl_add_u64 v[6:7], v[6:7], 0, v[66:67]
	global_load_dword v61, v[10:11], off
	global_load_dwordx4 v[36:39], v[8:9], off nt
	global_load_dwordx4 v[32:35], v[6:7], off nt
	global_load_dword v60, v[10:11], off offset:16
	s_add_u32 s38, s82, 0x1160000
	v_mad_i64_i32 v[70:71], s[0:1], v2, s15, 0
	v_mad_i64_i32 v[72:73], s[0:1], v3, s15, 0
	v_mad_i64_i32 v[74:75], s[0:1], v5, s15, 0
	v_mad_i64_i32 v[76:77], s[0:1], v4, s15, 0
	s_addc_u32 s39, s83, 0
	s_ashr_i32 s91, s90, 31
	s_lshl_b32 s20, s90, 1
	s_lshl_b32 s40, s86, 1
	s_ashr_i32 s13, s86, 31
	s_lshl_b64 s[0:1], s[90:91], 9
	s_add_u32 s0, s82, s0
	s_addc_u32 s1, s83, s1
	s_mov_b32 s12, s86
	v_mbcnt_hi_u32_b32 v82, -1, v215
	v_bfrev_b32_e32 v1, 0.5
	s_waitcnt vmcnt(4)
	v_mov_b64_e32 v[8:9], v[56:57]
	v_mov_b64_e32 v[4:5], v[40:41]
	v_mov_b64_e32 v[12:13], v[48:49]
	v_mov_b64_e32 v[16:17], v[52:53]
	v_mov_b64_e32 v[20:21], v[44:45]
	s_add_u32 s24, s0, 0x1600000
	s_mov_b64 s[14:15], 0x1000
	s_mov_b32 s19, 0xbfb8aa3b
	s_mov_b32 s30, 0x3f2aaaab
	v_mov_b32_e32 v78, 0x3ecc95a3
	s_mov_b32 s31, 0x3f317218
	s_mov_b32 s33, 0x7f800000
	s_mov_b32 s34, 0x33800000
	s_movk_i32 s35, 0x7f
	s_movk_i32 s36, 0x90
	s_movk_i32 s37, 0x110
	v_mov_b32_e32 v79, 0x7f800000
	v_mov_b32_e32 v80, 0x7fc00000
	v_mov_b32_e32 v81, 0xff800000
	v_mov_b64_e32 v[10:11], v[58:59]
	v_mov_b64_e32 v[6:7], v[42:43]
	v_mov_b64_e32 v[14:15], v[50:51]
	v_mov_b64_e32 v[18:19], v[54:55]
	v_mov_b64_e32 v[22:23], v[46:47]
	v_lshl_or_b32 v83, v82, 2, v1
	s_mov_b64 s[22:23], s[90:91]
	s_addc_u32 s25, s1, 0
	s_lshl_b64 s[26:27], s[12:13], 9
	s_add_i32 s41, 0, 0x14000
	s_waitcnt lgkmcnt(0)
	s_barrier
	s_waitcnt vmcnt(3)
	v_mov_b32_e32 v1, v61
	s_waitcnt vmcnt(2)
	v_mov_b64_e32 v[24:25], v[36:37]
	s_waitcnt vmcnt(1)
	v_mov_b64_e32 v[28:29], v[32:33]
	v_mov_b64_e32 v[26:27], v[38:39]
	v_mov_b64_e32 v[30:31], v[34:35]
	s_waitcnt vmcnt(0)
	v_mov_b32_e32 v65, v60
	s_branch .LBB0_361

.LBB0_361:
	s_add_i32 s0, s86, s22
	s_cmpk_gt_i32 s0, 0x7ff
	s_cbranch_scc1 .LBB0_371
	s_ashr_i32 s2, s0, 8
	s_and_b32 s28, s0, 63
	s_ashr_i32 s3, s2, 31
	s_bfe_u32 s4, s0, 0x20006
	s_lshl_b64 s[0:1], s[2:3], 12
	s_lshl_b32 s2, s28, 6
	s_or_b32 s0, s0, s2
	s_mul_i32 s2, s1, 0x2c00
	s_mul_hi_u32 s3, s0, 0x2c00
	s_add_i32 s3, s3, s2
	s_mul_i32 s2, s0, 0x2c00
	v_readlane_b32 s42, v246, 26
	v_readlane_b32 s43, v246, 27
	s_add_u32 s21, s42, s2
	s_addc_u32 s42, s43, s3
	s_lshl_b32 s2, s4, 8
	s_add_u32 s2, s21, s2
	s_addc_u32 s3, s42, 0
	v_mov_b32_e32 v65, v0
	s_cmp_lg_u32 s28, 0
	v_mov_b32_e32 v6, v0
	v_mov_b32_e32 v7, v0
	v_lshl_add_u64 v[2:3], s[2:3], 0, v[64:65]
	s_cselect_b64 s[2:3], -1, 0
	v_mov_b32_e32 v4, v0
	v_mov_b32_e32 v5, v0
	v_mov_b64_e32 v[10:11], v[6:7]
	v_lshl_add_u64 v[24:25], v[2:3], 0, s[14:15]
	s_or_b64 s[44:45], vcc, s[2:3]
	v_mov_b64_e32 v[8:9], v[4:5]
	s_and_saveexec_b64 s[28:29], s[44:45]
	s_cbranch_execz .LBB0_364
	v_lshl_add_u64 v[2:3], v[24:25], 0, v[72:73]
	global_load_dwordx4 v[8:11], v[2:3], off nt
.LBB0_364:
	s_or_b64 exec, exec, s[28:29]
	v_mov_b64_e32 v[14:15], v[6:7]
	s_or_b64 s[44:45], s[6:7], s[2:3]
	v_mov_b64_e32 v[12:13], v[4:5]
	s_and_saveexec_b64 s[28:29], s[44:45]
	s_cbranch_execz .LBB0_366
	v_lshl_add_u64 v[4:5], v[24:25], 0, v[74:75]
	v_lshl_add_u64 v[2:3], v[24:25], 0, v[76:77]
	global_load_dwordx4 v[4:7], v[4:5], off nt
	s_nop 0
	global_load_dwordx4 v[12:15], v[2:3], off nt
.LBB0_366:
	s_or_b64 exec, exec, s[28:29]
	v_mov_b32_e32 v2, v0
	v_mov_b32_e32 v3, v0
	v_mov_b32_e32 v1, v0
	v_mov_b64_e32 v[18:19], v[2:3]
	s_or_b64 s[2:3], s[8:9], s[2:3]
	v_mov_b64_e32 v[16:17], v[0:1]
	s_and_saveexec_b64 s[28:29], s[2:3]
	s_cbranch_execz .LBB0_368
	v_lshl_add_u64 v[16:17], v[24:25], 0, v[70:71]
	global_load_dwordx4 v[16:19], v[16:17], off nt
.LBB0_368:
	s_or_b64 exec, exec, s[28:29]
	v_mov_b64_e32 v[22:23], v[2:3]
	v_mov_b64_e32 v[20:21], v[0:1]
	s_and_saveexec_b64 s[28:29], s[2:3]
	s_cbranch_execz .LBB0_370
	v_lshl_add_u64 v[2:3], v[24:25], 0, v[66:67]
	global_load_dwordx4 v[20:23], v[2:3], off nt
.LBB0_370:
	s_or_b64 exec, exec, s[28:29]
	s_lshl_b32 s2, s4, 7
	s_lshl_b32 s2, s2, 1
	s_add_u32 s2, s21, s2
	s_addc_u32 s3, s42, 0
	v_mov_b32_e32 v65, v0
	v_lshl_add_u64 v[2:3], s[2:3], 0, v[64:65]
	v_lshl_add_u64 v[2:3], v[2:3], 0, s[10:11]
	v_lshl_add_u64 v[24:25], v[2:3], 0, v[70:71]
	v_lshl_add_u64 v[2:3], v[2:3], 0, v[66:67]
	global_load_dwordx4 v[24:27], v[24:25], off nt
	s_nop 0
	global_load_dwordx4 v[28:31], v[2:3], off nt
	v_mov_b32_e32 v3, s1
	v_or_b32_e32 v2, s0, v68
	v_readlane_b32 s0, v246, 24
	v_lshlrev_b64 v[2:3], 5, v[2:3]
	v_readlane_b32 s1, v246, 25
	s_lshl_b32 s4, s4, 2
	s_nop 0
	v_lshl_add_u64 v[2:3], s[0:1], 0, v[2:3]
	v_lshl_add_u64 v[2:3], v[2:3], 0, s[4:5]
	global_load_dword v1, v[2:3], off
	global_load_dword v65, v[2:3], off offset:16
